# v57 + P3 cross-chunk scan: the full vmcnt(0) drain after the first 27 loads replaced by counted waits at each load's first use (stores start while later loads are still in flight)
# baseline (speedup 1.0000x reference)
; DI unsigned pk2(float lo, float hi) { f32x2 v = {lo, hi}; return __builtin_bit_cast(unsigned, __builtin_convertvector(v, bf16x2v)); }
; DI float bflo(unsigned u) { return __uint_as_float(u << 16); }
; DI float bfhi(unsigned u) { return __uint_as_float(u & 0xffff0000u); }
; DI void ret_scan(const bf16_t* KV, bf16_t* SP, float* o_state, int gt, int nthreads) {
;     for (int e = gt; e < 65536; e += nthreads) {
;         const int h = e >> 14, dv = (e >> 6) & 255, dk4 = (e & 63) * 4;
;         const float lg = log1pf(-exp2f(-5.0f - (float)h)), Dc = __expf(128.0f * lg), c1 = __expf(127.0f * lg);
;         const size_t base = ((size_t)(h * 256 + dv)) * 256 + dk4;
;         f32x4 s = {0.f, 0.f, 0.f, 0.f};
;         for (int n0 = 0; n0 < 64; n0 += 32) {
;             u32x2 q[32];
; #pragma unroll
;             for (int u = 0; u < 32; ++u) q[u] = *(const u32x2*)(KV + (size_t)(n0 + u) * 262144 + base);
; #pragma unroll
;             for (int u = 0; u < 32; ++u) { u32x2 o; o.x = pk2(s[0], s[1]); o.y = pk2(s[2], s[3]); *(u32x2*)(SP + (size_t)(n0 + u) * 262144 + base) = o;
;                 const f32x4 kv = {bflo(q[u].x), bfhi(q[u].x), bflo(q[u].y), bfhi(q[u].y)}; s = s * Dc + kv * c1; }
;         }
.LBB0_308:
	v_cndmask_b32_e64 v20, 0, 1, s[18:19]
	s_lshl_b64 s[6:7], s[16:17], 1
	v_cmp_ne_u32_e32 vcc, 1, v20
	v_lshl_add_u64 v[20:21], v[8:9], 0, s[6:7]
	global_load_dwordx2 v[82:83], v[20:21], off
	s_or_b32 s0, s16, 0x40000
	s_mov_b32 s1, s17
	s_lshl_b64 s[8:9], s[0:1], 1
	v_lshl_add_u64 v[20:21], v[8:9], 0, s[8:9]
	s_or_b32 s0, s16, 0x80000
	global_load_dwordx2 v[80:81], v[20:21], off
	s_lshl_b64 s[4:5], s[0:1], 1
	v_lshl_add_u64 v[20:21], v[8:9], 0, s[4:5]
	s_or_b32 s0, s16, 0xc0000
	global_load_dwordx2 v[78:79], v[20:21], off
	s_lshl_b64 s[12:13], s[0:1], 1
	v_lshl_add_u64 v[20:21], v[8:9], 0, s[12:13]
	s_or_b32 s0, s16, 0x100000
	global_load_dwordx2 v[76:77], v[20:21], off
	s_lshl_b64 s[0:1], s[0:1], 1
	v_lshl_add_u64 v[20:21], v[8:9], 0, s[0:1]
	s_or_b32 s18, s16, 0x140000
	s_mov_b32 s19, s17
	global_load_dwordx2 v[74:75], v[20:21], off
	s_lshl_b64 s[96:97], s[18:19], 1
	v_lshl_add_u64 v[20:21], v[8:9], 0, s[96:97]
	s_or_b32 s18, s16, 0x180000
	global_load_dwordx2 v[72:73], v[20:21], off
	s_lshl_b64 s[94:95], s[18:19], 1
	v_lshl_add_u64 v[20:21], v[8:9], 0, s[94:95]
	s_or_b32 s18, s16, 0x1c0000
	global_load_dwordx2 v[70:71], v[20:21], off
	s_lshl_b64 s[92:93], s[18:19], 1
	v_lshl_add_u64 v[20:21], v[8:9], 0, s[92:93]
	s_or_b32 s18, s16, 0x200000
	global_load_dwordx2 v[68:69], v[20:21], off
	s_lshl_b64 s[90:91], s[18:19], 1
	v_lshl_add_u64 v[20:21], v[8:9], 0, s[90:91]
	s_or_b32 s18, s16, 0x240000
	global_load_dwordx2 v[66:67], v[20:21], off
	s_lshl_b64 s[88:89], s[18:19], 1
	v_lshl_add_u64 v[20:21], v[8:9], 0, s[88:89]
	s_or_b32 s18, s16, 0x280000
	global_load_dwordx2 v[64:65], v[20:21], off
	s_lshl_b64 s[86:87], s[18:19], 1
	v_lshl_add_u64 v[20:21], v[8:9], 0, s[86:87]
	s_or_b32 s18, s16, 0x2c0000
	global_load_dwordx2 v[62:63], v[20:21], off
	s_lshl_b64 s[84:85], s[18:19], 1
	v_lshl_add_u64 v[20:21], v[8:9], 0, s[84:85]
	s_or_b32 s18, s16, 0x300000
	global_load_dwordx2 v[60:61], v[20:21], off
	s_lshl_b64 s[82:83], s[18:19], 1
	v_lshl_add_u64 v[20:21], v[8:9], 0, s[82:83]
	s_or_b32 s18, s16, 0x340000
	global_load_dwordx2 v[58:59], v[20:21], off
	s_lshl_b64 s[80:81], s[18:19], 1
	v_lshl_add_u64 v[20:21], v[8:9], 0, s[80:81]
	s_or_b32 s18, s16, 0x380000
	global_load_dwordx2 v[56:57], v[20:21], off
	s_lshl_b64 s[78:79], s[18:19], 1
	v_lshl_add_u64 v[20:21], v[8:9], 0, s[78:79]
	s_or_b32 s18, s16, 0x3c0000
	global_load_dwordx2 v[54:55], v[20:21], off
	s_lshl_b64 s[76:77], s[18:19], 1
	v_lshl_add_u64 v[20:21], v[8:9], 0, s[76:77]
	s_or_b32 s18, s16, 0x400000
	global_load_dwordx2 v[52:53], v[20:21], off
	s_lshl_b64 s[74:75], s[18:19], 1
	v_lshl_add_u64 v[20:21], v[8:9], 0, s[74:75]
	s_or_b32 s18, s16, 0x440000
	global_load_dwordx2 v[50:51], v[20:21], off
	s_lshl_b64 s[72:73], s[18:19], 1
	v_lshl_add_u64 v[20:21], v[8:9], 0, s[72:73]
	s_or_b32 s18, s16, 0x480000
	global_load_dwordx2 v[48:49], v[20:21], off
	s_lshl_b64 s[70:71], s[18:19], 1
	v_lshl_add_u64 v[20:21], v[8:9], 0, s[70:71]
	s_or_b32 s18, s16, 0x4c0000
	global_load_dwordx2 v[46:47], v[20:21], off
	s_lshl_b64 s[68:69], s[18:19], 1
	v_lshl_add_u64 v[20:21], v[8:9], 0, s[68:69]
	s_or_b32 s18, s16, 0x500000
	global_load_dwordx2 v[44:45], v[20:21], off
	s_lshl_b64 s[42:43], s[18:19], 1
	v_lshl_add_u64 v[20:21], v[8:9], 0, s[42:43]
	s_or_b32 s18, s16, 0x540000
	global_load_dwordx2 v[42:43], v[20:21], off
	s_lshl_b64 s[40:41], s[18:19], 1
	v_lshl_add_u64 v[20:21], v[8:9], 0, s[40:41]
	s_or_b32 s18, s16, 0x580000
	global_load_dwordx2 v[40:41], v[20:21], off
	s_lshl_b64 s[38:39], s[18:19], 1
	v_lshl_add_u64 v[20:21], v[8:9], 0, s[38:39]
	s_or_b32 s18, s16, 0x5c0000
	global_load_dwordx2 v[38:39], v[20:21], off
	s_lshl_b64 s[36:37], s[18:19], 1
	v_lshl_add_u64 v[20:21], v[8:9], 0, s[36:37]
	s_or_b32 s18, s16, 0x600000
	global_load_dwordx2 v[36:37], v[20:21], off
	s_lshl_b64 s[34:35], s[18:19], 1
	v_lshl_add_u64 v[20:21], v[8:9], 0, s[34:35]
	s_or_b32 s18, s16, 0x640000
	global_load_dwordx2 v[34:35], v[20:21], off
	s_lshl_b64 s[30:31], s[18:19], 1
	v_lshl_add_u64 v[20:21], v[8:9], 0, s[30:31]
	s_or_b32 s18, s16, 0x680000
	global_load_dwordx2 v[32:33], v[20:21], off
	s_lshl_b64 s[28:29], s[18:19], 1
	v_lshl_add_u64 v[20:21], v[8:9], 0, s[28:29]
	s_or_b32 s18, s16, 0x6c0000
	global_load_dwordx2 v[30:31], v[20:21], off
	v_cvt_pk_bf16_f32 v92, v18, v19
	v_cvt_pk_bf16_f32 v93, v16, v17
	v_lshl_add_u64 v[94:95], v[10:11], 0, s[6:7]
	s_lshl_b64 s[26:27], s[18:19], 1
	global_store_dwordx2 v[94:95], v[92:93], off
	s_waitcnt vmcnt(27)
	v_lshlrev_b32_e32 v92, 16, v82
	v_and_b32_e32 v93, 0xffff0000, v82
	v_lshlrev_b32_e32 v82, 16, v83
	v_and_b32_e32 v83, 0xffff0000, v83
	v_lshl_add_u64 v[20:21], v[8:9], 0, s[26:27]
	v_pk_mul_f32 v[92:93], v[6:7], v[92:93]
	v_pk_mul_f32 v[82:83], v[14:15], v[82:83]
	s_or_b32 s18, s16, 0x700000
	global_load_dwordx2 v[28:29], v[20:21], off
	v_pk_fma_f32 v[16:17], v[12:13], v[16:17], v[82:83]
	v_pk_fma_f32 v[18:19], v[4:5], v[18:19], v[92:93]
	s_lshl_b64 s[24:25], s[18:19], 1
	v_cvt_pk_bf16_f32 v82, v18, v19
	v_cvt_pk_bf16_f32 v83, v16, v17
	v_lshl_add_u64 v[92:93], v[10:11], 0, s[8:9]
	v_lshl_add_u64 v[20:21], v[8:9], 0, s[24:25]
	global_store_dwordx2 v[92:93], v[82:83], off
	s_waitcnt vmcnt(28)
	v_lshlrev_b32_e32 v82, 16, v80
	v_and_b32_e32 v83, 0xffff0000, v80
	v_lshlrev_b32_e32 v80, 16, v81
	v_and_b32_e32 v81, 0xffff0000, v81
	v_pk_mul_f32 v[18:19], v[4:5], v[18:19]
	v_pk_mul_f32 v[16:17], v[12:13], v[16:17]
	s_or_b32 s18, s16, 0x740000
	global_load_dwordx2 v[26:27], v[20:21], off
	v_pk_fma_f32 v[16:17], v[14:15], v[80:81], v[16:17]
	v_pk_fma_f32 v[18:19], v[6:7], v[82:83], v[18:19]
	s_lshl_b64 s[22:23], s[18:19], 1
	v_cvt_pk_bf16_f32 v80, v18, v19
	v_cvt_pk_bf16_f32 v81, v16, v17
	v_lshl_add_u64 v[82:83], v[10:11], 0, s[4:5]
	v_lshl_add_u64 v[20:21], v[8:9], 0, s[22:23]
	global_store_dwordx2 v[82:83], v[80:81], off
	s_waitcnt vmcnt(29)
; DI unsigned pk2(float lo, float hi) { f32x2 v = {lo, hi}; return __builtin_bit_cast(unsigned, __builtin_convertvector(v, bf16x2v)); }
; DI float bflo(unsigned u) { return __uint_as_float(u << 16); }
; DI float bfhi(unsigned u) { return __uint_as_float(u & 0xffff0000u); }
; DI void ret_scan(const bf16_t* KV, bf16_t* SP, float* o_state, int gt, int nthreads) {
;     ...
;         for (int n0 = 0; n0 < 64; n0 += 32) {
;             u32x2 q[32];
; #pragma unroll
;             for (int u = 0; u < 32; ++u) q[u] = *(const u32x2*)(KV + (size_t)(n0 + u) * 262144 + base);
; #pragma unroll
;             for (int u = 0; u < 32; ++u) { u32x2 o; o.x = pk2(s[0], s[1]); o.y = pk2(s[2], s[3]); *(u32x2*)(SP + (size_t)(n0 + u) * 262144 + base) = o;
;                 const f32x4 kv = {bflo(q[u].x), bfhi(q[u].x), bflo(q[u].y), bfhi(q[u].y)}; s = s * Dc + kv * c1; }
;         }
	v_lshlrev_b32_e32 v80, 16, v78
	v_and_b32_e32 v81, 0xffff0000, v78
	v_lshlrev_b32_e32 v78, 16, v79
	v_and_b32_e32 v79, 0xffff0000, v79
	v_pk_mul_f32 v[18:19], v[4:5], v[18:19]
	v_pk_mul_f32 v[16:17], v[12:13], v[16:17]
	s_or_b32 s18, s16, 0x780000
	global_load_dwordx2 v[24:25], v[20:21], off
	v_pk_fma_f32 v[16:17], v[14:15], v[78:79], v[16:17]
	v_pk_fma_f32 v[18:19], v[6:7], v[80:81], v[18:19]
	s_lshl_b64 s[20:21], s[18:19], 1
	v_cvt_pk_bf16_f32 v78, v18, v19
	v_cvt_pk_bf16_f32 v79, v16, v17
	v_lshl_add_u64 v[80:81], v[10:11], 0, s[12:13]
	v_lshl_add_u64 v[20:21], v[8:9], 0, s[20:21]
	global_store_dwordx2 v[80:81], v[78:79], off
	s_waitcnt vmcnt(30)
	v_lshlrev_b32_e32 v78, 16, v76
	v_and_b32_e32 v79, 0xffff0000, v76
	v_lshlrev_b32_e32 v76, 16, v77
	v_and_b32_e32 v77, 0xffff0000, v77
	v_pk_mul_f32 v[18:19], v[4:5], v[18:19]
	v_pk_mul_f32 v[16:17], v[12:13], v[16:17]
	s_or_b32 s16, s16, 0x7c0000
	global_load_dwordx2 v[22:23], v[20:21], off
	v_pk_fma_f32 v[16:17], v[14:15], v[76:77], v[16:17]
	v_pk_fma_f32 v[18:19], v[6:7], v[78:79], v[18:19]
	s_lshl_b64 s[18:19], s[16:17], 1
	v_cvt_pk_bf16_f32 v76, v18, v19
	v_cvt_pk_bf16_f32 v77, v16, v17
	v_lshl_add_u64 v[78:79], v[10:11], 0, s[0:1]
	v_lshl_add_u64 v[20:21], v[8:9], 0, s[18:19]
	global_store_dwordx2 v[78:79], v[76:77], off
	s_waitcnt vmcnt(31)
	v_lshlrev_b32_e32 v76, 16, v74
	v_and_b32_e32 v77, 0xffff0000, v74
	v_lshlrev_b32_e32 v74, 16, v75
	v_and_b32_e32 v75, 0xffff0000, v75
	v_pk_mul_f32 v[18:19], v[4:5], v[18:19]
	v_pk_mul_f32 v[16:17], v[12:13], v[16:17]
	global_load_dwordx2 v[20:21], v[20:21], off
	v_pk_fma_f32 v[16:17], v[14:15], v[74:75], v[16:17]
	v_pk_fma_f32 v[18:19], v[6:7], v[76:77], v[18:19]
	v_cvt_pk_bf16_f32 v75, v16, v17
	v_cvt_pk_bf16_f32 v74, v18, v19
	v_lshl_add_u64 v[76:77], v[10:11], 0, s[96:97]
	global_store_dwordx2 v[76:77], v[74:75], off
	s_waitcnt vmcnt(32)
	v_lshlrev_b32_e32 v74, 16, v72
	v_and_b32_e32 v75, 0xffff0000, v72
	v_lshlrev_b32_e32 v72, 16, v73
	v_and_b32_e32 v73, 0xffff0000, v73
	v_pk_mul_f32 v[18:19], v[4:5], v[18:19]
	v_pk_mul_f32 v[16:17], v[12:13], v[16:17]
	v_pk_fma_f32 v[18:19], v[6:7], v[74:75], v[18:19]
	v_pk_fma_f32 v[16:17], v[14:15], v[72:73], v[16:17]
	v_cvt_pk_bf16_f32 v72, v18, v19
	v_cvt_pk_bf16_f32 v73, v16, v17
	v_lshl_add_u64 v[74:75], v[10:11], 0, s[94:95]
	global_store_dwordx2 v[74:75], v[72:73], off
	s_waitcnt vmcnt(32)
	v_lshlrev_b32_e32 v72, 16, v70
	v_and_b32_e32 v73, 0xffff0000, v70
	v_lshlrev_b32_e32 v70, 16, v71
	v_and_b32_e32 v71, 0xffff0000, v71
	v_pk_mul_f32 v[18:19], v[4:5], v[18:19]
	v_pk_mul_f32 v[16:17], v[12:13], v[16:17]
	v_pk_fma_f32 v[18:19], v[6:7], v[72:73], v[18:19]
	v_pk_fma_f32 v[16:17], v[14:15], v[70:71], v[16:17]
	v_cvt_pk_bf16_f32 v70, v18, v19
	v_cvt_pk_bf16_f32 v71, v16, v17
	v_lshl_add_u64 v[72:73], v[10:11], 0, s[92:93]
	global_store_dwordx2 v[72:73], v[70:71], off
	s_waitcnt vmcnt(32)
	v_lshlrev_b32_e32 v70, 16, v68
	v_and_b32_e32 v71, 0xffff0000, v68
	v_lshlrev_b32_e32 v68, 16, v69
	v_and_b32_e32 v69, 0xffff0000, v69
	v_pk_mul_f32 v[18:19], v[4:5], v[18:19]
	v_pk_mul_f32 v[16:17], v[12:13], v[16:17]
	v_pk_fma_f32 v[18:19], v[6:7], v[70:71], v[18:19]
	v_pk_fma_f32 v[16:17], v[14:15], v[68:69], v[16:17]
	v_cvt_pk_bf16_f32 v68, v18, v19
	v_cvt_pk_bf16_f32 v69, v16, v17
	v_lshl_add_u64 v[70:71], v[10:11], 0, s[90:91]
	global_store_dwordx2 v[70:71], v[68:69], off
	s_waitcnt vmcnt(32)
	v_lshlrev_b32_e32 v68, 16, v66
	v_and_b32_e32 v69, 0xffff0000, v66
	v_lshlrev_b32_e32 v66, 16, v67
	v_and_b32_e32 v67, 0xffff0000, v67
	v_pk_mul_f32 v[18:19], v[4:5], v[18:19]
	v_pk_mul_f32 v[16:17], v[12:13], v[16:17]
	v_pk_fma_f32 v[18:19], v[6:7], v[68:69], v[18:19]
	v_pk_fma_f32 v[16:17], v[14:15], v[66:67], v[16:17]
	v_cvt_pk_bf16_f32 v66, v18, v19
	v_cvt_pk_bf16_f32 v67, v16, v17
	v_lshl_add_u64 v[68:69], v[10:11], 0, s[88:89]
	global_store_dwordx2 v[68:69], v[66:67], off
	s_waitcnt vmcnt(32)
	v_lshlrev_b32_e32 v66, 16, v64
	v_and_b32_e32 v67, 0xffff0000, v64
	v_lshlrev_b32_e32 v64, 16, v65
	v_and_b32_e32 v65, 0xffff0000, v65
	v_pk_mul_f32 v[18:19], v[4:5], v[18:19]
	v_pk_mul_f32 v[16:17], v[12:13], v[16:17]
	v_pk_fma_f32 v[18:19], v[6:7], v[66:67], v[18:19]
	v_pk_fma_f32 v[16:17], v[14:15], v[64:65], v[16:17]
	v_cvt_pk_bf16_f32 v64, v18, v19
	v_cvt_pk_bf16_f32 v65, v16, v17
	v_lshl_add_u64 v[66:67], v[10:11], 0, s[86:87]
	global_store_dwordx2 v[66:67], v[64:65], off
	s_waitcnt vmcnt(32)
	v_lshlrev_b32_e32 v64, 16, v62
	v_and_b32_e32 v65, 0xffff0000, v62
	v_lshlrev_b32_e32 v62, 16, v63
	v_and_b32_e32 v63, 0xffff0000, v63
	v_pk_mul_f32 v[18:19], v[4:5], v[18:19]
	v_pk_mul_f32 v[16:17], v[12:13], v[16:17]
	v_pk_fma_f32 v[18:19], v[6:7], v[64:65], v[18:19]
	v_pk_fma_f32 v[16:17], v[14:15], v[62:63], v[16:17]
	v_cvt_pk_bf16_f32 v62, v18, v19
	v_cvt_pk_bf16_f32 v63, v16, v17
	v_lshl_add_u64 v[64:65], v[10:11], 0, s[84:85]
	global_store_dwordx2 v[64:65], v[62:63], off
	s_waitcnt vmcnt(32)
	v_lshlrev_b32_e32 v62, 16, v60
	v_and_b32_e32 v63, 0xffff0000, v60
	v_lshlrev_b32_e32 v60, 16, v61
	v_and_b32_e32 v61, 0xffff0000, v61
	v_pk_mul_f32 v[18:19], v[4:5], v[18:19]
	v_pk_mul_f32 v[16:17], v[12:13], v[16:17]
	v_pk_fma_f32 v[18:19], v[6:7], v[62:63], v[18:19]
	v_pk_fma_f32 v[16:17], v[14:15], v[60:61], v[16:17]
	v_cvt_pk_bf16_f32 v60, v18, v19
	v_cvt_pk_bf16_f32 v61, v16, v17
	v_lshl_add_u64 v[62:63], v[10:11], 0, s[82:83]
	global_store_dwordx2 v[62:63], v[60:61], off
	s_waitcnt vmcnt(32)
; DI unsigned pk2(float lo, float hi) { f32x2 v = {lo, hi}; return __builtin_bit_cast(unsigned, __builtin_convertvector(v, bf16x2v)); }
; DI float bflo(unsigned u) { return __uint_as_float(u << 16); }
; DI float bfhi(unsigned u) { return __uint_as_float(u & 0xffff0000u); }
; DI void ret_scan(const bf16_t* KV, bf16_t* SP, float* o_state, int gt, int nthreads) {
;     ...
;         for (int n0 = 0; n0 < 64; n0 += 32) {
;             u32x2 q[32];
; #pragma unroll
;             for (int u = 0; u < 32; ++u) q[u] = *(const u32x2*)(KV + (size_t)(n0 + u) * 262144 + base);
; #pragma unroll
;             for (int u = 0; u < 32; ++u) { u32x2 o; o.x = pk2(s[0], s[1]); o.y = pk2(s[2], s[3]); *(u32x2*)(SP + (size_t)(n0 + u) * 262144 + base) = o;
;                 const f32x4 kv = {bflo(q[u].x), bfhi(q[u].x), bflo(q[u].y), bfhi(q[u].y)}; s = s * Dc + kv * c1; }
;         }
	v_lshlrev_b32_e32 v60, 16, v58
	v_and_b32_e32 v61, 0xffff0000, v58
	v_lshlrev_b32_e32 v58, 16, v59
	v_and_b32_e32 v59, 0xffff0000, v59
	v_pk_mul_f32 v[18:19], v[4:5], v[18:19]
	v_pk_mul_f32 v[16:17], v[12:13], v[16:17]
	v_pk_fma_f32 v[18:19], v[6:7], v[60:61], v[18:19]
	v_pk_fma_f32 v[16:17], v[14:15], v[58:59], v[16:17]
	v_cvt_pk_bf16_f32 v58, v18, v19
	v_cvt_pk_bf16_f32 v59, v16, v17
	v_lshl_add_u64 v[60:61], v[10:11], 0, s[80:81]
	global_store_dwordx2 v[60:61], v[58:59], off
	s_waitcnt vmcnt(32)
	v_lshlrev_b32_e32 v58, 16, v56
	v_and_b32_e32 v59, 0xffff0000, v56
	v_lshlrev_b32_e32 v56, 16, v57
	v_and_b32_e32 v57, 0xffff0000, v57
	v_pk_mul_f32 v[18:19], v[4:5], v[18:19]
	v_pk_mul_f32 v[16:17], v[12:13], v[16:17]
	v_pk_fma_f32 v[18:19], v[6:7], v[58:59], v[18:19]
	v_pk_fma_f32 v[16:17], v[14:15], v[56:57], v[16:17]
	v_cvt_pk_bf16_f32 v56, v18, v19
	v_cvt_pk_bf16_f32 v57, v16, v17
	v_lshl_add_u64 v[58:59], v[10:11], 0, s[78:79]
	global_store_dwordx2 v[58:59], v[56:57], off
	s_waitcnt vmcnt(32)
	v_lshlrev_b32_e32 v56, 16, v54
	v_and_b32_e32 v57, 0xffff0000, v54
	v_lshlrev_b32_e32 v54, 16, v55
	v_and_b32_e32 v55, 0xffff0000, v55
	v_pk_mul_f32 v[18:19], v[4:5], v[18:19]
	v_pk_mul_f32 v[16:17], v[12:13], v[16:17]
	v_pk_fma_f32 v[18:19], v[6:7], v[56:57], v[18:19]
	v_pk_fma_f32 v[16:17], v[14:15], v[54:55], v[16:17]
	v_cvt_pk_bf16_f32 v54, v18, v19
	v_cvt_pk_bf16_f32 v55, v16, v17
	v_lshl_add_u64 v[56:57], v[10:11], 0, s[76:77]
	global_store_dwordx2 v[56:57], v[54:55], off
	s_waitcnt vmcnt(32)
	v_lshlrev_b32_e32 v54, 16, v52
	v_and_b32_e32 v55, 0xffff0000, v52
	v_lshlrev_b32_e32 v52, 16, v53
	v_and_b32_e32 v53, 0xffff0000, v53
	v_pk_mul_f32 v[18:19], v[4:5], v[18:19]
	v_pk_mul_f32 v[16:17], v[12:13], v[16:17]
	v_pk_fma_f32 v[18:19], v[6:7], v[54:55], v[18:19]
	v_pk_fma_f32 v[16:17], v[14:15], v[52:53], v[16:17]
	v_cvt_pk_bf16_f32 v52, v18, v19
	v_cvt_pk_bf16_f32 v53, v16, v17
	v_lshl_add_u64 v[54:55], v[10:11], 0, s[74:75]
	global_store_dwordx2 v[54:55], v[52:53], off
	s_waitcnt vmcnt(32)
	v_lshlrev_b32_e32 v52, 16, v50
	v_and_b32_e32 v53, 0xffff0000, v50
	v_lshlrev_b32_e32 v50, 16, v51
	v_and_b32_e32 v51, 0xffff0000, v51
	v_pk_mul_f32 v[18:19], v[4:5], v[18:19]
	v_pk_mul_f32 v[16:17], v[12:13], v[16:17]
	v_pk_fma_f32 v[18:19], v[6:7], v[52:53], v[18:19]
	v_pk_fma_f32 v[16:17], v[14:15], v[50:51], v[16:17]
	v_cvt_pk_bf16_f32 v50, v18, v19
	v_cvt_pk_bf16_f32 v51, v16, v17
	v_lshl_add_u64 v[52:53], v[10:11], 0, s[72:73]
	global_store_dwordx2 v[52:53], v[50:51], off
	s_waitcnt vmcnt(32)
	v_lshlrev_b32_e32 v50, 16, v48
	v_and_b32_e32 v51, 0xffff0000, v48
	v_lshlrev_b32_e32 v48, 16, v49
	v_and_b32_e32 v49, 0xffff0000, v49
	v_pk_mul_f32 v[18:19], v[4:5], v[18:19]
	v_pk_mul_f32 v[16:17], v[12:13], v[16:17]
	v_pk_fma_f32 v[18:19], v[6:7], v[50:51], v[18:19]
	v_pk_fma_f32 v[16:17], v[14:15], v[48:49], v[16:17]
	v_cvt_pk_bf16_f32 v48, v18, v19
	v_cvt_pk_bf16_f32 v49, v16, v17
	v_lshl_add_u64 v[50:51], v[10:11], 0, s[70:71]
	global_store_dwordx2 v[50:51], v[48:49], off
	s_waitcnt vmcnt(32)
	v_lshlrev_b32_e32 v48, 16, v46
	v_and_b32_e32 v49, 0xffff0000, v46
	v_lshlrev_b32_e32 v46, 16, v47
	v_and_b32_e32 v47, 0xffff0000, v47
	v_pk_mul_f32 v[18:19], v[4:5], v[18:19]
	v_pk_mul_f32 v[16:17], v[12:13], v[16:17]
	v_pk_fma_f32 v[18:19], v[6:7], v[48:49], v[18:19]
	v_pk_fma_f32 v[16:17], v[14:15], v[46:47], v[16:17]
	v_cvt_pk_bf16_f32 v46, v18, v19
	v_cvt_pk_bf16_f32 v47, v16, v17
	v_lshl_add_u64 v[48:49], v[10:11], 0, s[68:69]
	global_store_dwordx2 v[48:49], v[46:47], off
	s_waitcnt vmcnt(32)
	v_lshlrev_b32_e32 v46, 16, v44
	v_and_b32_e32 v47, 0xffff0000, v44
	v_lshlrev_b32_e32 v44, 16, v45
	v_and_b32_e32 v45, 0xffff0000, v45
	v_pk_mul_f32 v[18:19], v[4:5], v[18:19]
	v_pk_mul_f32 v[16:17], v[12:13], v[16:17]
	v_pk_fma_f32 v[18:19], v[6:7], v[46:47], v[18:19]
	v_pk_fma_f32 v[16:17], v[14:15], v[44:45], v[16:17]
	v_cvt_pk_bf16_f32 v44, v18, v19
	v_cvt_pk_bf16_f32 v45, v16, v17
	v_lshl_add_u64 v[46:47], v[10:11], 0, s[42:43]
	global_store_dwordx2 v[46:47], v[44:45], off
	s_waitcnt vmcnt(32)
	v_lshlrev_b32_e32 v44, 16, v42
	v_and_b32_e32 v45, 0xffff0000, v42
	v_lshlrev_b32_e32 v42, 16, v43
	v_and_b32_e32 v43, 0xffff0000, v43
	v_pk_mul_f32 v[18:19], v[4:5], v[18:19]
	v_pk_mul_f32 v[16:17], v[12:13], v[16:17]
	v_pk_fma_f32 v[18:19], v[6:7], v[44:45], v[18:19]
	v_pk_fma_f32 v[16:17], v[14:15], v[42:43], v[16:17]
	v_cvt_pk_bf16_f32 v42, v18, v19
	v_cvt_pk_bf16_f32 v43, v16, v17
	v_lshl_add_u64 v[44:45], v[10:11], 0, s[40:41]
	global_store_dwordx2 v[44:45], v[42:43], off
	s_waitcnt vmcnt(32)
	v_lshlrev_b32_e32 v42, 16, v40
	v_and_b32_e32 v43, 0xffff0000, v40
	v_lshlrev_b32_e32 v40, 16, v41
	v_and_b32_e32 v41, 0xffff0000, v41
	v_pk_mul_f32 v[18:19], v[4:5], v[18:19]
	v_pk_mul_f32 v[16:17], v[12:13], v[16:17]
	v_pk_fma_f32 v[18:19], v[6:7], v[42:43], v[18:19]
	v_pk_fma_f32 v[16:17], v[14:15], v[40:41], v[16:17]
	v_cvt_pk_bf16_f32 v40, v18, v19
	v_cvt_pk_bf16_f32 v41, v16, v17
	v_lshl_add_u64 v[42:43], v[10:11], 0, s[38:39]
	global_store_dwordx2 v[42:43], v[40:41], off
	s_waitcnt vmcnt(32)
	v_lshlrev_b32_e32 v40, 16, v38
	v_and_b32_e32 v41, 0xffff0000, v38
	v_lshlrev_b32_e32 v38, 16, v39
	v_and_b32_e32 v39, 0xffff0000, v39
	v_pk_mul_f32 v[18:19], v[4:5], v[18:19]
	v_pk_mul_f32 v[16:17], v[12:13], v[16:17]
	v_pk_fma_f32 v[18:19], v[6:7], v[40:41], v[18:19]
	v_pk_fma_f32 v[16:17], v[14:15], v[38:39], v[16:17]
	v_cvt_pk_bf16_f32 v38, v18, v19
	v_cvt_pk_bf16_f32 v39, v16, v17
	v_lshl_add_u64 v[40:41], v[10:11], 0, s[36:37]
	global_store_dwordx2 v[40:41], v[38:39], off
	s_waitcnt vmcnt(32)
; DI unsigned pk2(float lo, float hi) { f32x2 v = {lo, hi}; return __builtin_bit_cast(unsigned, __builtin_convertvector(v, bf16x2v)); }
; DI float bflo(unsigned u) { return __uint_as_float(u << 16); }
; DI float bfhi(unsigned u) { return __uint_as_float(u & 0xffff0000u); }
; DI void ret_scan(const bf16_t* KV, bf16_t* SP, float* o_state, int gt, int nthreads) {
;     ...
;         for (int n0 = 0; n0 < 64; n0 += 32) {
;             u32x2 q[32];
; #pragma unroll
;             for (int u = 0; u < 32; ++u) q[u] = *(const u32x2*)(KV + (size_t)(n0 + u) * 262144 + base);
; #pragma unroll
;             for (int u = 0; u < 32; ++u) { u32x2 o; o.x = pk2(s[0], s[1]); o.y = pk2(s[2], s[3]); *(u32x2*)(SP + (size_t)(n0 + u) * 262144 + base) = o;
;                 const f32x4 kv = {bflo(q[u].x), bfhi(q[u].x), bflo(q[u].y), bfhi(q[u].y)}; s = s * Dc + kv * c1; }
;         }
; #pragma unroll
;         for (int j = 0; j < 4; ++j) o_state[((size_t)(h * 256 + dk4 + j)) * 256 + dv] = s[j];
;     }
	v_lshlrev_b32_e32 v38, 16, v36
	v_and_b32_e32 v39, 0xffff0000, v36
	v_lshlrev_b32_e32 v36, 16, v37
	v_and_b32_e32 v37, 0xffff0000, v37
	v_pk_mul_f32 v[18:19], v[4:5], v[18:19]
	v_pk_mul_f32 v[16:17], v[12:13], v[16:17]
	v_pk_fma_f32 v[18:19], v[6:7], v[38:39], v[18:19]
	v_pk_fma_f32 v[16:17], v[14:15], v[36:37], v[16:17]
	v_cvt_pk_bf16_f32 v36, v18, v19
	v_cvt_pk_bf16_f32 v37, v16, v17
	v_lshl_add_u64 v[38:39], v[10:11], 0, s[34:35]
	global_store_dwordx2 v[38:39], v[36:37], off
	s_waitcnt vmcnt(32)
	v_lshlrev_b32_e32 v36, 16, v34
	v_and_b32_e32 v37, 0xffff0000, v34
	v_lshlrev_b32_e32 v34, 16, v35
	v_and_b32_e32 v35, 0xffff0000, v35
	v_pk_mul_f32 v[18:19], v[4:5], v[18:19]
	v_pk_mul_f32 v[16:17], v[12:13], v[16:17]
	v_pk_fma_f32 v[18:19], v[6:7], v[36:37], v[18:19]
	v_pk_fma_f32 v[16:17], v[14:15], v[34:35], v[16:17]
	v_cvt_pk_bf16_f32 v34, v18, v19
	v_cvt_pk_bf16_f32 v35, v16, v17
	v_lshl_add_u64 v[36:37], v[10:11], 0, s[30:31]
	global_store_dwordx2 v[36:37], v[34:35], off
	s_waitcnt vmcnt(32)
	v_lshlrev_b32_e32 v34, 16, v32
	v_and_b32_e32 v35, 0xffff0000, v32
	v_lshlrev_b32_e32 v32, 16, v33
	v_and_b32_e32 v33, 0xffff0000, v33
	v_pk_mul_f32 v[18:19], v[4:5], v[18:19]
	v_pk_mul_f32 v[16:17], v[12:13], v[16:17]
	v_pk_fma_f32 v[18:19], v[6:7], v[34:35], v[18:19]
	v_pk_fma_f32 v[16:17], v[14:15], v[32:33], v[16:17]
	v_cvt_pk_bf16_f32 v32, v18, v19
	v_cvt_pk_bf16_f32 v33, v16, v17
	v_lshl_add_u64 v[34:35], v[10:11], 0, s[28:29]
	global_store_dwordx2 v[34:35], v[32:33], off
	s_waitcnt vmcnt(32)
	v_lshlrev_b32_e32 v32, 16, v30
	v_and_b32_e32 v33, 0xffff0000, v30
	v_lshlrev_b32_e32 v30, 16, v31
	v_and_b32_e32 v31, 0xffff0000, v31
	v_pk_mul_f32 v[18:19], v[4:5], v[18:19]
	v_pk_mul_f32 v[16:17], v[12:13], v[16:17]
	v_pk_fma_f32 v[18:19], v[6:7], v[32:33], v[18:19]
	v_pk_fma_f32 v[16:17], v[14:15], v[30:31], v[16:17]
	v_cvt_pk_bf16_f32 v30, v18, v19
	v_cvt_pk_bf16_f32 v31, v16, v17
	v_lshl_add_u64 v[32:33], v[10:11], 0, s[26:27]
	global_store_dwordx2 v[32:33], v[30:31], off
	s_waitcnt vmcnt(31)
	v_lshlrev_b32_e32 v30, 16, v28
	v_and_b32_e32 v31, 0xffff0000, v28
	v_lshlrev_b32_e32 v28, 16, v29
	v_and_b32_e32 v29, 0xffff0000, v29
	v_pk_mul_f32 v[18:19], v[4:5], v[18:19]
	v_pk_mul_f32 v[16:17], v[12:13], v[16:17]
	v_pk_fma_f32 v[18:19], v[6:7], v[30:31], v[18:19]
	v_pk_fma_f32 v[16:17], v[14:15], v[28:29], v[16:17]
	v_cvt_pk_bf16_f32 v28, v18, v19
	v_cvt_pk_bf16_f32 v29, v16, v17
	v_lshl_add_u64 v[30:31], v[10:11], 0, s[24:25]
	global_store_dwordx2 v[30:31], v[28:29], off
	s_waitcnt vmcnt(30)
	v_lshlrev_b32_e32 v28, 16, v26
	v_and_b32_e32 v29, 0xffff0000, v26
	v_lshlrev_b32_e32 v26, 16, v27
	v_and_b32_e32 v27, 0xffff0000, v27
	v_pk_mul_f32 v[18:19], v[4:5], v[18:19]
	v_pk_mul_f32 v[16:17], v[12:13], v[16:17]
	v_pk_fma_f32 v[18:19], v[6:7], v[28:29], v[18:19]
	v_pk_fma_f32 v[16:17], v[14:15], v[26:27], v[16:17]
	v_cvt_pk_bf16_f32 v26, v18, v19
	v_cvt_pk_bf16_f32 v27, v16, v17
	v_lshl_add_u64 v[28:29], v[10:11], 0, s[22:23]
	global_store_dwordx2 v[28:29], v[26:27], off
	s_waitcnt vmcnt(29)
	v_lshlrev_b32_e32 v26, 16, v24
	v_and_b32_e32 v27, 0xffff0000, v24
	v_lshlrev_b32_e32 v24, 16, v25
	v_and_b32_e32 v25, 0xffff0000, v25
	v_pk_mul_f32 v[18:19], v[4:5], v[18:19]
	v_pk_mul_f32 v[16:17], v[12:13], v[16:17]
	v_pk_fma_f32 v[18:19], v[6:7], v[26:27], v[18:19]
	v_pk_fma_f32 v[16:17], v[14:15], v[24:25], v[16:17]
	v_cvt_pk_bf16_f32 v24, v18, v19
	v_cvt_pk_bf16_f32 v25, v16, v17
	v_lshl_add_u64 v[26:27], v[10:11], 0, s[20:21]
	global_store_dwordx2 v[26:27], v[24:25], off
	s_waitcnt vmcnt(28)
	v_lshlrev_b32_e32 v24, 16, v22
	v_and_b32_e32 v25, 0xffff0000, v22
	v_lshlrev_b32_e32 v22, 16, v23
	v_and_b32_e32 v23, 0xffff0000, v23
	v_pk_mul_f32 v[18:19], v[4:5], v[18:19]
	v_pk_mul_f32 v[16:17], v[12:13], v[16:17]
	v_pk_fma_f32 v[18:19], v[6:7], v[24:25], v[18:19]
	v_pk_fma_f32 v[16:17], v[14:15], v[22:23], v[16:17]
	v_cvt_pk_bf16_f32 v22, v18, v19
	v_cvt_pk_bf16_f32 v23, v16, v17
	v_lshl_add_u64 v[24:25], v[10:11], 0, s[18:19]
	global_store_dwordx2 v[24:25], v[22:23], off
	s_waitcnt vmcnt(27)
	v_lshlrev_b32_e32 v22, 16, v20
	v_and_b32_e32 v23, 0xffff0000, v20
	v_lshlrev_b32_e32 v20, 16, v21
	v_and_b32_e32 v21, 0xffff0000, v21
	v_pk_mul_f32 v[18:19], v[4:5], v[18:19]
	v_pk_mul_f32 v[16:17], v[12:13], v[16:17]
	v_pk_fma_f32 v[18:19], v[6:7], v[22:23], v[18:19]
	v_pk_fma_f32 v[16:17], v[14:15], v[20:21], v[16:17]
	s_mov_b32 s16, 0x800000
	s_mov_b64 s[18:19], 0
	s_cbranch_vccz .LBB0_308
	v_or_b32_e32 v4, v3, v90
	v_lshlrev_b32_e32 v0, 2, v0
	v_ashrrev_i32_e32 v5, 31, v4
	v_lshl_add_u64 v[6:7], s[10:11], 0, v[0:1]
	v_lshlrev_b64 v[8:9], 10, v[4:5]
	v_lshl_add_u64 v[8:9], v[6:7], 0, v[8:9]
	global_store_dword v[8:9], v18, off
	v_or_b32_e32 v8, 1, v4
	v_ashrrev_i32_e32 v9, 31, v8
	v_lshlrev_b64 v[8:9], 10, v[8:9]
	v_lshl_add_u64 v[8:9], v[6:7], 0, v[8:9]
	global_store_dword v[8:9], v19, off
	v_or_b32_e32 v8, 2, v4
	v_or_b32_e32 v4, 3, v4
	v_ashrrev_i32_e32 v9, 31, v8
	v_ashrrev_i32_e32 v5, 31, v4
	v_add_u32_e32 v84, s33, v84
	s_mov_b32 s0, 0xffff
	v_lshlrev_b64 v[8:9], 10, v[8:9]
	v_lshlrev_b64 v[4:5], 10, v[4:5]
	v_cmp_lt_i32_e32 vcc, s0, v84
	v_lshl_add_u64 v[8:9], v[6:7], 0, v[8:9]
	v_lshl_add_u64 v[4:5], v[6:7], 0, v[4:5]
	s_or_b64 s[14:15], vcc, s[14:15]
	global_store_dword v[8:9], v16, off
	global_store_dword v[4:5], v17, off
	s_andn2_b64 exec, exec, s[14:15]
	s_cbranch_execnz .LBB0_307
